# combo9 + DPP reduction ladders, K-loops at the same placement mod 128 as combo9 (extra 64 B pad after the prologue)
# baseline (speedup 1.0000x reference)
.LBB0_101:
	s_nop 0
	s_nop 0
	s_nop 0
	s_nop 0
	s_nop 0
	s_nop 0
	s_nop 0
	s_nop 0
	s_nop 0
	s_nop 0
	s_nop 0
	s_nop 0
	s_nop 0
	s_nop 0
	s_nop 0
	s_nop 0
	s_nop 0
	s_nop 0
	s_nop 0
	s_nop 0
	s_nop 0
	s_nop 0
	s_nop 0
	s_nop 0
	s_nop 0
	s_nop 0
	s_nop 0
	s_nop 0
	s_mov_b32 s0, -1
	s_waitcnt vmcnt(0)
	s_barrier
	s_nop 0
	v_mbcnt_lo_u32_b32 v0, s0, 0
	v_mbcnt_hi_u32_b32 v0, s0, v0
	v_add_u32_e32 v0, s76, v0
	s_nop 0
	v_cmp_eq_u32_e32 vcc, 0, v0
	s_and_saveexec_b64 s[4:5], vcc
	s_cbranch_execz .LBB0_153
	s_add_i32 s1, 0, 0x22160
	v_mov_b32_e32 v0, s1
	s_getreg_b32 s0, hwreg(HW_REG_XCC_ID, 0, 4)
	s_waitcnt vmcnt(0) expcnt(0) lgkmcnt(0)
	ds_read_b32 v2, v0
	s_add_i32 s1, 0, 0x22164
	v_mov_b32_e32 v0, s1
	ds_read_b32 v0, v0
	s_and_b32 s3, s0, 15
	s_waitcnt lgkmcnt(1)
	v_cmp_ne_u32_e32 vcc, 0, v2
	s_cbranch_vccnz .LBB0_117
	s_add_u32 s6, s12, 0x4200
	s_addc_u32 s7, s13, 0
	s_add_u32 s8, s12, 0x4400
	s_addc_u32 s9, s13, 0
	s_add_u32 s10, s12, 0x4500
	s_addc_u32 s11, s13, 0
	s_add_u32 s16, s12, 0x4600
	s_addc_u32 s17, s13, 0
	s_add_u32 s18, s12, 0x4700
	s_addc_u32 s19, s13, 0
	s_add_u32 s20, s12, 0x4800
	s_addc_u32 s21, s13, 0
	s_add_u32 s22, s12, 0x4900
	s_addc_u32 s23, s13, 0
	s_add_u32 s30, s12, 0x4a00
	s_addc_u32 s31, s13, 0
	s_add_u32 s34, s12, 0x4b00
	s_addc_u32 s35, s13, 0
	s_add_u32 s36, s12, 0x4c00
	s_addc_u32 s37, s13, 0
	s_add_u32 s38, s12, 0x4d00
	s_addc_u32 s39, s13, 0
	s_add_u32 s40, s12, 0x4e00
	s_addc_u32 s41, s13, 0
	s_add_u32 s42, s12, 0x4f00
	s_addc_u32 s43, s13, 0
	s_add_u32 s44, s12, 0x5000
	s_addc_u32 s45, s13, 0
	s_add_u32 s46, s12, 0x5100
	s_addc_u32 s47, s13, 0
	s_add_u32 s48, s12, 0x5200
	s_addc_u32 s49, s13, 0
	s_add_u32 s50, s12, 0x5300
	s_addc_u32 s51, s13, 0
	s_mov_b32 s0, 1
	v_mov_b32_e32 v16, 0
	s_movk_i32 s1, 0x100
	s_branch .LBB0_105
